# CT state buffer stored in MFMA-fragment order (scan stores + mlstm_out loads lane-quad coalesced) on top of k-inner MFMA order, setprio removed, mid_opt LDS conflict fix
# speedup vs baseline: 1.0218x; 1.0039x over previous
.LBB0_478:
	s_cmp_lt_i32 s70, 5
	s_cselect_b64 s[2:3], -1, 0
	s_and_b64 s[38:39], s[2:3], s[0:1]
	s_andn2_b64 vcc, exec, s[38:39]
	s_cbranch_vccnz .LBB0_521
	v_and_b32_e32 v1, 7, v0
	s_cmpk_gt_i32 s94, 0xff
	v_lshrrev_b32_e32 v188, 4, v163
	v_and_b32_e32 v162, 15, v0
	v_and_b32_e32 v189, 3, v0
	v_lshrrev_b32_e32 v190, 6, v0
	s_cbranch_scc1 .LBB0_499
	s_waitcnt vmcnt(0)
	v_and_b32_e32 v9, 0xc0, v0
	v_mov_b32_e32 v164, 0
	v_lshrrev_b32_e32 v4, 2, v0
	v_and_or_b32 v192, v4, 64, v162
	v_lshlrev_b32_e32 v4, 5, v9
	v_mov_b32_e32 v5, v164
	v_and_b32_e32 v6, 48, v0
	v_lshl_add_u64 v[4:5], s[68:69], 0, v[4:5]
	v_lshlrev_b32_e32 v6, 5, v6
	v_mov_b32_e32 v7, v164
	v_lshl_add_u64 v[4:5], v[4:5], 0, v[6:7]
	s_mov_b64 s[2:3], 0x1000000
	v_lshl_add_u64 v[166:167], v[4:5], 0, s[2:3]
	v_lshlrev_b32_e32 v4, 2, v0
	v_and_b32_e32 v11, 48, v4
	v_lshlrev_b32_e32 v4, 2, v11
	v_mov_b32_e32 v5, v164
	v_lshl_add_u64 v[4:5], s[68:69], 0, v[4:5]
	v_lshlrev_b32_e32 v6, 2, v189
	v_lshrrev_b32_e32 v2, 4, v0
	v_lshl_add_u64 v[4:5], v[4:5], 0, v[6:7]
	v_lshlrev_b32_e32 v6, 2, v9
	v_and_b32_e32 v3, 24, v2
	v_lshl_add_u64 v[4:5], v[4:5], 0, v[6:7]
	s_mov_b64 s[8:9], 0x700000
	s_add_u32 s4, s68, 0x45000000
	v_or_b32_e32 v191, v3, v1
	v_lshl_add_u64 v[168:169], v[4:5], 0, s[8:9]
	v_lshlrev_b32_e32 v4, 8, v188
	s_addc_u32 s5, s69, 0
	v_or3_b32 v4, v4, v11, v9
	v_or_b32_e32 v7, 32, v191
	v_or_b32_e32 v11, 0x60, v191
	s_add_u32 s22, s68, 0x600000
	v_bfe_u32 v8, v0, 3, 4
	s_movk_i32 s6, 0xc0
	v_and_b32_e32 v6, 4, v190
	v_lshrrev_b32_e32 v9, 2, v7
	v_lshrrev_b32_e32 v12, 2, v11
	s_movk_i32 s8, 0x80
	s_addc_u32 s23, s69, 0
	v_lshlrev_b32_e32 v2, 3, v8
	v_lshl_add_u32 v10, v8, 12, 0
	v_bitop3_b32 v3, v3, v6, v1 bitop3:0x36
	v_bitop3_b32 v7, v9, v7, 12 bitop3:0x6c
	v_bitop3_b32 v9, v191, v6, 64 bitop3:0x36
	v_bitop3_b32 v11, v12, v11, 12 bitop3:0x6c
	v_bitop3_b32 v12, v191, v6, s8 bitop3:0x36
	v_bitop3_b32 v6, v191, v6, s6 bitop3:0x36
	v_lshlrev_b32_e32 v8, 11, v8
	s_add_i32 s6, 0, 0x10000
	v_lshlrev_b32_e32 v25, 11, v188
	v_add_u32_e32 v16, s6, v8
	v_add_u32_e32 v27, s6, v25
	s_add_i32 s6, 0, 0x10100
	v_add_u32_e32 v28, s6, v25
	s_add_i32 s6, 0, 0x10300
	v_add_u32_e32 v30, s6, v25
	s_add_i32 s6, 0, 0x12000
	v_add_u32_e32 v35, s6, v25
	s_add_i32 s6, 0, 0x12100
	v_add_u32_e32 v36, s6, v25
	s_add_i32 s6, 0, 0x12200
	v_add_u32_e32 v37, s6, v25
	s_add_i32 s6, 0, 0x12300
	v_add_u32_e32 v38, s6, v25
	s_add_i32 s6, 0, 0x14000
	v_add_u32_e32 v43, s6, v25
	s_add_i32 s6, 0, 0x14100
	v_and_b32_e32 v5, 12, v0
	v_add_u32_e32 v44, s6, v25
	s_add_i32 s6, 0, 0x14200
	v_or_b32_e32 v13, 0xa0, v191
	v_bitop3_b32 v20, v189, v5, 4 bitop3:0x36
	v_bitop3_b32 v5, v189, v5, 8 bitop3:0x36
	v_bitop3_b32 v23, v189, v0, 12 bitop3:0x72
	v_add_u32_e32 v45, s6, v25
	s_add_i32 s6, 0, 0x14300
	v_lshrrev_b32_e32 v14, 2, v13
	v_or_b32_e32 v19, v4, v162
	v_or_b32_e32 v21, v4, v20
	v_or_b32_e32 v22, v4, v5
	v_or_b32_e32 v24, v4, v23
	v_or_b32_e32 v31, 0x400, v4
	v_or_b32_e32 v39, 0x800, v4
	v_add_u32_e32 v46, s6, v25
	v_or_b32_e32 v4, 0xc00, v4
	s_add_i32 s6, 0, 0x16000
	v_bitop3_b32 v13, v14, v13, 12 bitop3:0x6c
	v_or_b32_e32 v14, 0xe0, v191
	v_or_b32_e32 v32, v31, v162
	v_or_b32_e32 v33, v31, v20
	v_or_b32_e32 v34, v31, v5
	v_or_b32_e32 v31, v31, v23
	v_or_b32_e32 v40, v39, v162
	v_or_b32_e32 v41, v39, v20
	v_or_b32_e32 v42, v39, v5
	v_or_b32_e32 v39, v39, v23
	v_or_b32_e32 v47, v4, v162
	v_or_b32_e32 v20, v4, v20
	v_or_b32_e32 v5, v4, v5
	v_or_b32_e32 v4, v4, v23
	v_add_u32_e32 v23, s6, v25
	s_add_i32 s6, 0, 0x16100
	v_lshrrev_b32_e32 v15, 2, v14
	s_add_i32 s9, 0, 0x10400
	v_add_u32_e32 v48, s6, v25
	s_add_i32 s6, 0, 0x16200
	v_bitop3_b32 v14, v15, v14, 12 bitop3:0x6c
	s_add_i32 s8, 0, 0x10200
	v_add_u32_e32 v18, s9, v8
	s_add_i32 s9, 0, 0x10600
	v_add_u32_e32 v49, s6, v25
	s_add_i32 s6, 0, 0x16300
	s_movk_i32 s0, 0x100
	v_lshlrev_b32_e32 v3, 4, v3
	v_lshlrev_b32_e32 v7, 4, v7
	v_lshlrev_b32_e32 v9, 4, v9
	v_lshlrev_b32_e32 v11, 4, v11
	v_lshlrev_b32_e32 v12, 4, v12
	v_lshlrev_b32_e32 v13, 4, v13
	v_lshlrev_b32_e32 v6, 4, v6
	v_lshlrev_b32_e32 v14, 4, v14
	v_lshlrev_b32_e32 v15, 4, v191
	v_add_u32_e32 v17, s8, v8
	v_add_u32_e32 v8, s9, v8
	v_lshlrev_b32_e32 v19, 4, v19
	v_lshlrev_b32_e32 v21, 4, v21
	v_lshlrev_b32_e32 v22, 4, v22
	v_lshlrev_b32_e32 v24, 4, v24
	v_lshlrev_b32_e32 v26, 4, v192
	v_add_u32_e32 v29, s8, v25
	v_lshlrev_b32_e32 v32, 4, v32
	v_lshlrev_b32_e32 v33, 4, v33
	v_lshlrev_b32_e32 v34, 4, v34
	v_lshlrev_b32_e32 v31, 4, v31
	v_lshlrev_b32_e32 v40, 4, v40
	v_lshlrev_b32_e32 v41, 4, v41
	v_lshlrev_b32_e32 v42, 4, v42
	v_lshlrev_b32_e32 v39, 4, v39
	v_lshlrev_b32_e32 v47, 4, v47
	v_lshlrev_b32_e32 v20, 4, v20
	v_lshlrev_b32_e32 v5, 4, v5
	v_lshlrev_b32_e32 v4, 4, v4
	v_add_u32_e32 v25, s6, v25
	v_lshlrev_b32_e32 v170, 1, v2
	v_mbcnt_lo_u32_b32 v2, -1, 0
	v_cmp_gt_u32_e64 s[0:1], s0, v0
	s_mov_b32 s7, 0
	v_cmp_gt_u32_e64 s[2:3], 16, v163
	s_mov_b32 s24, 0x61000000
	s_movk_i32 s25, 0x2000
	s_movk_i32 s26, 0x4000
	s_movk_i32 s27, 0x6000
	s_mov_b32 s28, 0x8000
	s_mov_b32 s29, 0xa000
	s_mov_b32 s30, 0xc000
	s_mov_b32 s31, 0xe000
	s_mov_b32 s34, 0x100000
	s_mov_b32 s35, 0x200000
	s_mov_b32 s36, 0x300000
	v_add_u32_e32 v193, v10, v3
	v_add_u32_e32 v194, v10, v7
	v_add_u32_e32 v195, v10, v9
	v_add_u32_e32 v196, v10, v11
	v_add_u32_e32 v197, v10, v12
	v_add_u32_e32 v198, v10, v13
	v_add_u32_e32 v199, v10, v6
	v_add_u32_e32 v200, v10, v14
	v_add_u32_e32 v201, v16, v15
	v_add_u32_e32 v202, v17, v15
	v_add_u32_e32 v203, v18, v15
	v_add_u32_e32 v204, v8, v15
	v_add_u32_e32 v205, 0, v19
	v_add_u32_e32 v206, 0, v21
	v_add_u32_e32 v207, 0, v22
	v_add_u32_e32 v208, 0, v24
	v_add_u32_e32 v209, v27, v26
	v_add_u32_e32 v210, v28, v26
	v_add_u32_e32 v211, v29, v26
	v_add_u32_e32 v212, v30, v26
	v_add_u32_e32 v213, 0, v32
	v_add_u32_e32 v214, 0, v33
	v_add_u32_e32 v215, 0, v34
	v_add_u32_e32 v216, 0, v31
	v_add_u32_e32 v217, v35, v26
	v_add_u32_e32 v218, v36, v26
	v_add_u32_e32 v219, v37, v26
	v_add_u32_e32 v220, v38, v26
	v_add_u32_e32 v221, 0, v40
	v_add_u32_e32 v222, 0, v41
	v_add_u32_e32 v223, 0, v42
	v_add_u32_e32 v224, 0, v39
	v_add_u32_e32 v225, v43, v26
	v_add_u32_e32 v226, v44, v26
	v_add_u32_e32 v227, v45, v26
	v_add_u32_e32 v228, v46, v26
	v_add_u32_e32 v229, 0, v47
	v_add_u32_e32 v230, 0, v20
	v_add_u32_e32 v231, 0, v5
	v_add_u32_e32 v232, 0, v4
	v_add_u32_e32 v233, v23, v26
	v_add_u32_e32 v234, v48, v26
	v_add_u32_e32 v235, v49, v26
	v_add_u32_e32 v236, v25, v26
	v_mbcnt_hi_u32_b32 v237, -1, v2
	s_mov_b32 s37, s94
	s_branch .LBB0_482

.LBB0_482:
	s_bfe_u32 s12, s37, 0x20005
	s_bfe_u32 s13, s37, 0x30002
	s_and_b32 s14, s37, 3
	s_cmpk_lt_u32 s37, 0x80
	s_cselect_b64 s[8:9], -1, 0
	s_and_b64 s[10:11], s[8:9], exec
	s_cselect_b32 s6, s24, 0x65000000
	s_cselect_b32 s15, 0, 31
	s_cselect_b32 s41, 1, -1
	s_add_u32 s10, s68, s6
	s_addc_u32 s11, s69, 0
	s_lshl_b32 s6, s12, 16
	s_lshl_b32 s16, s13, 8
	s_or_b32 s6, s6, s16
	s_lshl_b32 s16, s14, 7
	v_lshl_or_b32 v4, s13, 9, v191
	v_or_b32_e32 v2, s6, v191
	v_or_b32_e32 v4, s16, v4
	v_lshlrev_b32_e32 v2, 8, v2
	v_mov_b32_e32 v3, v164
	v_lshlrev_b32_e32 v4, 15, v4
	v_mov_b32_e32 v5, v164
	s_lshl_b32 s6, s12, 13
	v_lshl_add_u64 v[2:3], s[10:11], 0, v[2:3]
	v_lshl_add_u64 v[4:5], s[4:5], 0, v[4:5]
	v_mov_b32_e32 v171, v164
	s_cmp_eq_u32 s14, 0
	v_lshl_add_u64 v[4:5], v[4:5], 0, s[6:7]
	v_lshl_add_u64 v[172:173], v[2:3], 0, v[170:171]
	s_cselect_b64 s[10:11], -1, 0
	s_lshl_b32 s6, s15, 19
	v_lshl_add_u64 v[26:27], v[172:173], 0, s[6:7]
	v_add_co_u32_e32 v6, vcc, s25, v26
	v_lshl_add_u64 v[174:175], v[4:5], 0, v[170:171]
	s_nop 0
	v_addc_co_u32_e32 v7, vcc, 0, v27, vcc
	v_add_co_u32_e32 v10, vcc, s26, v26
	s_lshl_b32 s6, s15, 8
	s_nop 0
	v_addc_co_u32_e32 v11, vcc, 0, v27, vcc
	v_add_co_u32_e32 v14, vcc, s27, v26
	v_lshl_add_u64 v[42:43], v[174:175], 0, s[6:7]
	s_nop 0
	v_addc_co_u32_e32 v15, vcc, 0, v27, vcc
	v_add_co_u32_e32 v18, vcc, s28, v26
	s_ashr_i32 s6, s37, 5
	s_nop 0
	v_addc_co_u32_e32 v19, vcc, 0, v27, vcc
	v_add_co_u32_e32 v22, vcc, s29, v26
	s_and_b32 s6, s6, -4
	s_nop 0
	v_addc_co_u32_e32 v23, vcc, 0, v27, vcc
	v_add_co_u32_e32 v28, vcc, s30, v26
	s_or_b32 s14, s6, s12
	s_nop 0
	v_addc_co_u32_e32 v29, vcc, 0, v27, vcc
	v_add_co_u32_e32 v30, vcc, s31, v26
	s_lshl_b32 s6, s14, 8
	s_nop 0
	v_addc_co_u32_e32 v31, vcc, 0, v27, vcc
	s_lshl_b32 s17, s13, 5
	v_add_co_u32_e32 v38, vcc, s34, v42
	s_or_b32 s12, s6, s17
	s_nop 0
	v_addc_co_u32_e32 v39, vcc, 0, v43, vcc
	s_ashr_i32 s13, s12, 31
	v_add_co_u32_e32 v44, vcc, s35, v42
	s_and_b64 s[10:11], s[10:11], s[0:1]
	s_lshl_b64 s[12:13], s[12:13], 2
	v_addc_co_u32_e32 v45, vcc, 0, v43, vcc
	s_add_u32 s12, s22, s12
	v_add_co_u32_e32 v46, vcc, s36, v42
	s_addc_u32 s13, s23, s13
	s_lshl_b32 s6, s15, 2
	v_addc_co_u32_e32 v47, vcc, 0, v43, vcc
	v_mov_b32_e32 v50, s6
	global_load_dwordx4 v[2:5], v[26:27], off
	s_nop 0
	global_load_dwordx4 v[6:9], v[6:7], off
	s_nop 0
	global_load_dwordx4 v[10:13], v[10:11], off
	s_nop 0
	global_load_dwordx4 v[14:17], v[14:15], off
	s_nop 0
	global_load_dwordx4 v[18:21], v[18:19], off
	s_nop 0
	global_load_dwordx4 v[22:25], v[22:23], off
	s_nop 0
	global_load_dwordx4 v[26:29], v[28:29], off
	s_nop 0
	global_load_dwordx4 v[30:33], v[30:31], off
	s_nop 0
	global_load_dwordx4 v[34:37], v[42:43], off
	s_nop 0
	global_load_dwordx4 v[38:41], v[38:39], off
	s_nop 0
	global_load_dwordx4 v[42:45], v[44:45], off
	s_nop 0
	global_load_dwordx4 v[46:49], v[46:47], off
	s_ashr_i32 s15, s14, 31
	global_load_dword v182, v50, s[12:13]
	v_and_b32_e32 v50, 64, v192
	v_or_b32_e32 v50, s16, v50
	s_lshl_b64 s[14:15], s[14:15], 8
	v_lshlrev_b32_e32 v50, 9, v50
	v_and_b32_e32 v51, 15, v192
	v_lshl_or_b32 v50, v51, 4, v50
	v_mov_b32_e32 v51, v164
	v_mov_b32_e32 v165, v164
	s_mov_b32 s40, 31
	s_or_b32 s14, s14, s17
	s_and_b64 s[16:17], s[10:11], s[2:3]
	v_lshl_add_u64 v[176:177], v[166:167], 0, v[50:51]
	s_mov_b32 s6, 0
	v_mov_b64_e32 v[178:179], v[164:165]
	v_mov_b64_e32 v[180:181], v[164:165]
	v_mov_b32_e32 v50, v164
	v_mov_b32_e32 v52, v164
	v_mov_b32_e32 v53, v164
	v_mov_b32_e32 v54, v164
	v_mov_b32_e32 v55, v164
	v_mov_b32_e32 v56, v164
	v_mov_b32_e32 v57, v164
	v_mov_b32_e32 v58, v164
	v_mov_b32_e32 v59, v164
	v_mov_b32_e32 v60, v164
	v_mov_b32_e32 v61, v164
	v_mov_b32_e32 v62, v164
	v_mov_b32_e32 v63, v164
	v_mov_b32_e32 v64, v164
	v_mov_b32_e32 v65, v164
	v_mov_b32_e32 v66, v164
	v_mov_b32_e32 v67, v164
	v_mov_b32_e32 v68, v164
	v_mov_b32_e32 v69, v164
	v_mov_b32_e32 v70, v164
	v_mov_b32_e32 v71, v164
	v_mov_b32_e32 v72, v164
	v_mov_b32_e32 v73, v164
	v_mov_b32_e32 v74, v164
	v_mov_b32_e32 v75, v164
	v_mov_b32_e32 v76, v164
	v_mov_b32_e32 v77, v164
	v_mov_b32_e32 v78, v164
	v_mov_b32_e32 v79, v164
	v_mov_b32_e32 v80, v164
	v_mov_b32_e32 v81, v164
	v_mov_b32_e32 v82, v164
	v_mov_b32_e32 v83, v164
	v_mov_b32_e32 v84, v164
	v_mov_b32_e32 v85, v164
	v_mov_b32_e32 v86, v164
	v_mov_b32_e32 v87, v164
	v_mov_b32_e32 v88, v164
	v_mov_b32_e32 v89, v164
	v_mov_b32_e32 v90, v164
	v_mov_b32_e32 v91, v164
	v_mov_b32_e32 v92, v164
	v_mov_b32_e32 v93, v164
	v_mov_b32_e32 v94, v164
	v_mov_b32_e32 v95, v164
	v_mov_b32_e32 v96, v164
	v_mov_b32_e32 v97, v164
	v_mov_b32_e32 v98, v164
	v_mov_b32_e32 v99, v164
	v_mov_b32_e32 v100, v164
	v_mov_b32_e32 v101, v164
	v_mov_b32_e32 v102, v164
	v_mov_b32_e32 v103, v164
	v_mov_b32_e32 v104, v164
	v_mov_b32_e32 v105, v164
	v_mov_b32_e32 v106, v164
	v_mov_b32_e32 v107, v164
	v_mov_b32_e32 v108, v164
	v_mov_b32_e32 v109, v164
	v_mov_b32_e32 v110, v164
	v_mov_b32_e32 v111, v164
	v_mov_b32_e32 v112, v164
	v_mov_b32_e32 v113, v164
	s_barrier
	s_branch .LBB0_484

.LBB0_489:
	s_add_u32 s18, s14, s42
	s_addc_u32 s19, s15, 0
	s_lshl_b64 s[20:21], s[18:19], 18
	v_lshl_add_u64 v[122:123], v[176:177], 0, s[20:21]
	v_cvt_pk_bf16_f32 v114, v110, v111
	v_cvt_pk_bf16_f32 v115, v112, v113
	v_cvt_pk_bf16_f32 v116, v94, v95
	v_cvt_pk_bf16_f32 v117, v96, v97
	v_add_co_u32_e32 v124, vcc, s25, v122
	v_cvt_pk_bf16_f32 v118, v78, v79
	v_cvt_pk_bf16_f32 v119, v80, v81
	v_cvt_pk_bf16_f32 v120, v62, v63
	v_cvt_pk_bf16_f32 v121, v64, v65
	global_store_dwordx4 v[122:123], v[114:117], off
	global_store_dwordx4 v[122:123], v[118:121], off offset:256
	v_addc_co_u32_e32 v125, vcc, 0, v123, vcc
	v_cvt_pk_bf16_f32 v114, v106, v107
	v_cvt_pk_bf16_f32 v115, v108, v109
	v_cvt_pk_bf16_f32 v116, v90, v91
	v_cvt_pk_bf16_f32 v117, v92, v93
	s_nop 0
	v_cvt_pk_bf16_f32 v118, v74, v75
	v_cvt_pk_bf16_f32 v119, v76, v77
	v_cvt_pk_bf16_f32 v120, v58, v59
	v_cvt_pk_bf16_f32 v121, v60, v61
	global_store_dwordx4 v[124:125], v[114:117], off
	global_store_dwordx4 v[124:125], v[118:121], off offset:256
	v_add_co_u32_e32 v124, vcc, s26, v122
	v_cvt_pk_bf16_f32 v114, v102, v103
	v_cvt_pk_bf16_f32 v115, v104, v105
	v_cvt_pk_bf16_f32 v116, v86, v87
	v_cvt_pk_bf16_f32 v117, v88, v89
	s_nop 1
	v_addc_co_u32_e32 v125, vcc, 0, v123, vcc
	v_add_co_u32_e32 v122, vcc, 0x6000, v122
	v_cvt_pk_bf16_f32 v118, v70, v71
	v_cvt_pk_bf16_f32 v119, v72, v73
	v_cvt_pk_bf16_f32 v120, v54, v55
	v_cvt_pk_bf16_f32 v121, v56, v57
	global_store_dwordx4 v[124:125], v[114:117], off
	global_store_dwordx4 v[124:125], v[118:121], off offset:256
	v_addc_co_u32_e32 v123, vcc, 0, v123, vcc
	v_cvt_pk_bf16_f32 v114, v98, v99
	v_cvt_pk_bf16_f32 v115, v100, v101
	v_cvt_pk_bf16_f32 v116, v82, v83
	v_cvt_pk_bf16_f32 v117, v84, v85
	s_nop 0
	v_cvt_pk_bf16_f32 v118, v66, v67
	v_cvt_pk_bf16_f32 v119, v68, v69
	v_cvt_pk_bf16_f32 v120, v50, v51
	v_cvt_pk_bf16_f32 v121, v52, v53
	global_store_dwordx4 v[122:123], v[114:117], off
	global_store_dwordx4 v[122:123], v[118:121], off offset:256
	s_and_saveexec_b64 s[20:21], s[16:17]
	s_cbranch_execz .LBB0_491
	s_lshl_b64 s[18:19], s[18:19], 10
	v_lshl_add_u64 v[114:115], v[168:169], 0, s[18:19]
	global_store_dword v[114:115], v178, off
	global_store_dword v[114:115], v179, off offset:16
	global_store_dword v[114:115], v180, off offset:32
	global_store_dword v[114:115], v181, off offset:48

.LBB0_575:
	s_cmp_lt_i32 s70, 6
	s_cselect_b64 s[2:3], -1, 0
	s_and_b64 s[2:3], s[2:3], s[0:1]
	s_andn2_b64 vcc, exec, s[2:3]
	s_cbranch_vccnz .LBB0_598
	v_writelane_b32 v254, s2, 31
	s_cmpk_gt_i32 s94, 0x7ff
	s_nop 0
	v_writelane_b32 v254, s3, 32
	v_writelane_b32 v254, s96, 28
	s_nop 1
	v_writelane_b32 v254, s97, 29
	v_writelane_b32 v254, s94, 30
	s_cbranch_scc1 .LBB0_597
	s_add_u32 s52, s68, 0x55000000
	s_addc_u32 s53, s69, 0
	s_add_u32 s0, s68, 0x400000
	s_addc_u32 s1, s69, 0
	v_writelane_b32 v254, s0, 33
	s_waitcnt vmcnt(0)
	v_lshlrev_b32_e32 v10, 2, v0
	v_and_b32_e32 v7, 0x1c3, v0
	v_writelane_b32 v254, s1, 34
	s_add_u32 s0, s68, 0x500000
	s_addc_u32 s1, s69, 0
	v_and_or_b32 v1, v10, 48, v7
	v_writelane_b32 v254, s0, 35
	s_add_u32 s85, s68, 0x2d000000
	v_and_b32_e32 v148, 0x1fc, v1
	v_lshlrev_b32_e32 v148, 9, v148
	v_and_b32_e32 v5, 3, v1
	v_lshl_or_b32 v148, v5, 4, v148
	v_mov_b32_e32 v149, 0
	v_writelane_b32 v254, s1, 36
	s_addc_u32 s0, s69, 0
	v_lshl_add_u64 v[4:5], s[68:69], 0, v[148:149]
	v_and_b32_e32 v148, 48, v163
	v_lshlrev_b32_e32 v148, 4, v148
	v_writelane_b32 v254, s0, 26
	v_lshl_add_u64 v[4:5], v[4:5], 0, v[148:149]
	s_mov_b64 s[0:1], 0x1000000
	v_lshl_add_u64 v[150:151], v[4:5], 0, s[0:1]
	v_bfe_u32 v5, v0, 6, 1
	v_and_b32_e32 v146, 15, v0
	v_lshrrev_b32_e32 v6, 4, v163
	v_lshrrev_b32_e32 v9, 2, v0
	s_movk_i32 s0, 0x60
	v_lshlrev_b32_e32 v12, 6, v5
	v_and_or_b32 v11, v9, s0, v146
	v_or_b32_e32 v13, v12, v146
	v_lshl_or_b32 v12, v6, 2, v12
	v_cmp_ge_u32_e64 s[0:1], v12, v11
	v_or_b32_e32 v18, 1, v12
	v_or_b32_e32 v19, 2, v12
	v_writelane_b32 v254, s0, 37
	v_or_b32_e32 v20, 3, v12
	v_or_b32_e32 v21, 16, v12
	v_writelane_b32 v254, s1, 38
	v_cmp_le_u32_e64 s[0:1], v12, v11
	v_or_b32_e32 v22, 18, v12
	v_or_b32_e32 v23, 19, v12
	v_writelane_b32 v254, s0, 39
	v_or_b32_e32 v24, 32, v12
	v_or_b32_e32 v25, 33, v12
	v_writelane_b32 v254, s1, 40
	v_cmp_ge_u32_e64 s[0:1], v18, v11
	v_or_b32_e32 v26, 34, v12
	v_or_b32_e32 v27, 35, v12
	v_writelane_b32 v254, s0, 41
	v_or_b32_e32 v28, 48, v12
	v_or_b32_e32 v29, 49, v12
	v_writelane_b32 v254, s1, 42
	v_cmp_lt_u32_e64 s[0:1], v12, v11
	v_or_b32_e32 v30, 50, v12
	v_or_b32_e32 v31, 51, v12
	v_writelane_b32 v254, s0, 43
	v_or_b32_e32 v16, 16, v11
	v_lshlrev_b32_e32 v8, 3, v6
	v_writelane_b32 v254, s1, 44
	v_cmp_ge_u32_e64 s[0:1], v19, v11
	v_lshlrev_b32_e32 v14, 9, v5
	s_add_i32 s38, 0, 0x10800
	v_writelane_b32 v254, s0, 45
	v_lshlrev_b32_e32 v5, 7, v5
	s_add_i32 s39, 0, 0x21600
	v_writelane_b32 v254, s1, 46
	v_cmp_le_u32_e64 s[0:1], v19, v11
	v_add3_u32 v6, s38, v8, v5
	s_add_i32 s43, 0, 0x21000
	v_writelane_b32 v254, s0, 47
	v_lshlrev_b32_e32 v8, 2, v146
	v_or_b32_e32 v152, 16, v146
	v_writelane_b32 v254, s1, 48
	v_cmp_ge_u32_e64 s[0:1], v20, v11
	s_add_i32 s45, 0, 0x21400
	v_add_u32_e32 v147, s43, v8
	v_writelane_b32 v254, s0, 49
	v_or_b32_e32 v154, 32, v146
	v_add_u32_e32 v159, s45, v8
	v_writelane_b32 v254, s1, 50
	v_cmp_le_u32_e64 s[0:1], v20, v11
	v_add_u32_e32 v161, s39, v8
	v_lshlrev_b32_e32 v8, 2, v152
	v_writelane_b32 v254, s0, 51
	v_or_b32_e32 v156, 48, v146
	v_add_u32_e32 v165, s45, v8
	v_writelane_b32 v254, s1, 52
	v_cmp_ge_u32_e64 s[0:1], v21, v11
	v_add_u32_e32 v167, s39, v8
	v_lshlrev_b32_e32 v8, 2, v154
	v_writelane_b32 v254, s0, 53
	v_or_b32_e32 v158, 64, v146
	v_add_u32_e32 v169, s43, v8
	v_writelane_b32 v254, s1, 54
	v_cmp_le_u32_e64 s[0:1], v21, v11
	v_or_b32_e32 v21, 17, v12
	v_add_u32_e32 v171, s45, v8
	v_writelane_b32 v254, s0, 55
	v_add_u32_e32 v173, s39, v8
	v_lshlrev_b32_e32 v8, 2, v156
	v_writelane_b32 v254, s1, 56
	v_cmp_ge_u32_e64 s[0:1], v21, v11
	v_or_b32_e32 v160, 0x50, v146
	v_add_u32_e32 v175, s43, v8
	v_writelane_b32 v254, s0, 57
	v_add_u32_e32 v177, s45, v8
	v_add_u32_e32 v179, s39, v8
	v_writelane_b32 v254, s1, 58
	v_cmp_le_u32_e64 s[0:1], v21, v11
	v_lshlrev_b32_e32 v8, 2, v158
	v_or_b32_e32 v162, 0x60, v146
	v_writelane_b32 v254, s0, 59
	v_add_u32_e32 v181, s43, v8
	v_add_u32_e32 v196, s45, v8
	v_writelane_b32 v254, s1, 60
	v_cmp_ge_u32_e64 s[0:1], v22, v11
	v_add_u32_e32 v197, s39, v8
	v_lshlrev_b32_e32 v8, 2, v160
	v_writelane_b32 v254, s0, 61
	v_or_b32_e32 v164, 0x70, v146
	v_add_u32_e32 v198, s43, v8
	v_writelane_b32 v254, s1, 62
	v_cmp_le_u32_e64 s[0:1], v22, v11
	v_add_u32_e32 v199, s45, v8
	v_add_u32_e32 v200, s39, v8
	v_writelane_b32 v254, s0, 63
	v_lshlrev_b32_e32 v8, 2, v162
	v_add_u32_e32 v201, s43, v8
	v_writelane_b32 v255, s1, 0
	v_cmp_ge_u32_e64 s[0:1], v23, v11
	v_add_u32_e32 v202, s45, v8
	v_add_u32_e32 v203, s39, v8
	v_writelane_b32 v255, s0, 1
	v_lshlrev_b32_e32 v8, 2, v164
	v_cmp_ge_u32_e64 s[88:89], v21, v16
	v_writelane_b32 v255, s1, 2
	v_cmp_le_u32_e64 s[0:1], v23, v11
	v_cmp_le_u32_e64 s[90:91], v21, v16
	v_cmp_le_u32_e64 s[6:7], v24, v16
	v_writelane_b32 v255, s0, 3
	v_cmp_ge_u32_e64 s[16:17], v27, v16
	v_cmp_le_u32_e64 s[18:19], v27, v16
	v_writelane_b32 v255, s1, 4
	v_cmp_ge_u32_e64 s[0:1], v24, v11
	v_add_u32_e32 v204, s43, v8
	v_add_u32_e32 v205, s45, v8
	v_writelane_b32 v255, s0, 5
	v_add_u32_e32 v206, s39, v8
	v_and_b32_e32 v8, 31, v0
	v_writelane_b32 v255, s1, 6
	v_cmp_le_u32_e64 s[0:1], v24, v11
	v_or_b32_e32 v21, 0x600, v0
	s_movk_i32 s46, 0xc0
	v_writelane_b32 v255, s0, 7
	s_movk_i32 s42, 0x210
	v_lshrrev_b32_e32 v166, 5, v0
	v_writelane_b32 v255, s1, 8
	v_cmp_ge_u32_e64 s[0:1], v25, v11
	v_lshlrev_b32_e32 v168, 3, v8
	v_lshlrev_b32_e32 v207, 4, v8
	v_writelane_b32 v255, s0, 9
	v_mov_b32_e32 v8, s38
	v_lshrrev_b32_e32 v174, 5, v21
	v_writelane_b32 v255, s1, 10
	v_cmp_le_u32_e64 s[0:1], v25, v11
	v_cmp_gt_u32_e64 s[46:47], s46, v0
	v_cmp_ge_u32_e64 s[92:93], v22, v16
	v_writelane_b32 v255, s0, 11
	v_cmp_le_u32_e64 s[94:95], v22, v16
	v_cmp_ge_u32_e64 s[8:9], v25, v16
	v_writelane_b32 v255, s1, 12
	v_cmp_ge_u32_e64 s[0:1], v26, v11
	v_cmp_le_u32_e64 s[10:11], v25, v16
	v_cmp_ge_u32_e64 s[20:21], v28, v16
	v_writelane_b32 v255, s0, 13
	v_cmp_le_u32_e64 s[22:23], v28, v16
	v_mad_u32_u24 v208, v166, s42, v8
	v_writelane_b32 v255, s1, 14
	v_cmp_le_u32_e64 s[0:1], v26, v11
	v_mad_u32_u24 v22, v174, s42, v8
	v_add_u32_e32 v148, 0xfffffe00, v10
	v_writelane_b32 v255, s0, 15
	v_cmp_ge_u32_e64 s[24:25], v29, v16
	v_cmp_le_u32_e64 s[26:27], v29, v16
	v_writelane_b32 v255, s1, 16
	v_cmp_ge_u32_e64 s[0:1], v27, v11
	v_cmp_ge_u32_e64 s[28:29], v30, v16
	v_cmp_le_u32_e64 s[30:31], v30, v16
	v_writelane_b32 v255, s0, 17
	v_cmp_ge_u32_e64 s[34:35], v31, v16
	v_cmp_le_u32_e64 s[36:37], v31, v16
	v_writelane_b32 v255, s1, 18
	v_cmp_le_u32_e64 s[0:1], v27, v11
	v_or_b32_e32 v27, 0xe00, v0
	v_lshrrev_b32_e32 v182, 5, v27
	v_writelane_b32 v255, s0, 19
	s_add_i32 s44, 0, 0x21200
	v_lshl_add_u32 v157, v16, 2, s44
	v_writelane_b32 v255, s1, 20
	v_cmp_ge_u32_e64 s[0:1], v28, v11
	v_cmp_le_u32_e64 s[86:87], v20, v16
	v_cmp_ge_u32_e64 s[96:97], v23, v16
	v_writelane_b32 v255, s0, 21
	v_cmp_le_u32_e64 s[2:3], v23, v16
	v_cmp_ge_u32_e64 s[12:13], v26, v16
	v_writelane_b32 v255, s1, 22
	v_cmp_le_u32_e64 s[0:1], v28, v11
	v_mad_u32_u24 v28, v182, s42, v8
	v_cmp_le_u32_e64 s[14:15], v26, v16
	v_writelane_b32 v255, s0, 23
	v_add_u32_e32 v210, s43, v10
	v_add_u32_e32 v211, s44, v10
	v_writelane_b32 v255, s1, 24
	v_cmp_ge_u32_e64 s[0:1], v29, v11
	v_mul_u32_u24_e32 v10, 0x110, v16
	v_and_b32_e32 v4, 48, v0
	v_writelane_b32 v255, s0, 25
	s_cmpk_eq_i32 s33, 0x100
	v_mov_b32_e32 v5, v149
	v_writelane_b32 v255, s1, 26
	v_cmp_le_u32_e64 s[0:1], v29, v11
	v_lshlrev_b32_e32 v17, 2, v11
	s_cselect_b64 s[58:59], -1, 0
	v_writelane_b32 v255, s0, 27
	v_lshlrev_b32_e32 v7, 9, v7
	v_and_b32_e32 v2, 0x1c0, v0
	v_writelane_b32 v255, s1, 28
	v_cmp_ge_u32_e64 s[0:1], v30, v11
	v_add_u32_e32 v3, 0, v4
	v_mul_u32_u24_e32 v15, 0x210, v11
	v_writelane_b32 v255, s0, 29
	v_mul_u32_u24_e32 v13, 0x210, v13
	v_add_u32_e32 v153, s44, v17
	v_writelane_b32 v255, s1, 30
	v_cmp_le_u32_e64 s[0:1], v30, v11
	v_mad_u32_u24 v30, v9, s42, 0
	v_add3_u32 v155, s39, v14, v17
	v_writelane_b32 v255, s0, 31
	v_mul_u32_u24_e32 v14, 0x110, v146
	v_mad_u32_u24 v17, v166, s42, 0
	v_writelane_b32 v255, s1, 32
	v_cmp_ge_u32_e64 s[0:1], v31, v11
	v_mad_u32_u24 v21, v174, s42, 0
	v_add_u32_e32 v23, 0x8400, v208
	v_writelane_b32 v255, s0, 33
	v_add_u32_e32 v26, 0xc600, v208
	v_mad_u32_u24 v27, v182, s42, 0
	v_writelane_b32 v255, s1, 34
	v_cmp_le_u32_e64 s[0:1], v31, v11
	v_mul_u32_u24_e32 v11, 0x110, v11
	s_movk_i32 s38, 0x7f
	v_writelane_b32 v255, s0, 35
	v_cmp_gt_u32_e64 s[4:5], 16, v163
	v_or_b32_e32 v172, 32, v166
	v_writelane_b32 v255, s1, 36
	v_cmp_ge_u32_e64 s[0:1], v12, v16
	v_or_b32_e32 v176, 64, v166
	v_or_b32_e32 v180, 0x60, v166
	v_writelane_b32 v255, s0, 37
	v_cmp_lt_u32_e64 s[38:39], s38, v0
	v_add3_u32 v217, v13, v4, 0
	v_writelane_b32 v255, s1, 38
	v_cmp_le_u32_e64 s[0:1], v12, v16
	v_add3_u32 v218, v15, v4, 0
	v_add3_u32 v220, v14, v4, 0
	v_writelane_b32 v255, s0, 39
	v_add_u32_e32 v221, v17, v207
	v_add_u32_e32 v225, v21, v207
	v_writelane_b32 v255, s1, 40
	v_cmp_ge_u32_e64 s[0:1], v18, v16
	v_or_b32_e32 v18, 0x200, v0
	v_lshrrev_b32_e32 v170, 5, v18
	v_writelane_b32 v255, s0, 41
	v_mad_u32_u24 v18, v170, s42, 0
	v_add_u32_e32 v222, v18, v207
	v_writelane_b32 v255, s1, 42
	v_cmp_lt_u32_e64 s[0:1], v12, v16
	v_mul_u32_u24_e32 v12, 0x210, v146
	v_add_u32_e32 v226, v22, v207
	v_writelane_b32 v255, s0, 43
	v_add_u32_e32 v227, v23, v207
	v_add_u32_e32 v230, v26, v207
	v_writelane_b32 v255, s1, 44
	v_cmp_ge_u32_e64 s[0:1], v19, v16
	v_add_u32_e32 v231, v27, v207
	v_add_u32_e32 v232, v28, v207
	v_writelane_b32 v255, s0, 45
	v_add_u32_e32 v235, v6, v11
	v_add_u32_e32 v236, v6, v10
	v_writelane_b32 v255, s1, 46
	v_cmp_le_u32_e64 s[0:1], v19, v16
	v_mad_u32_u24 v19, v170, s42, v8
	v_add_u32_e32 v223, v19, v207
	v_writelane_b32 v255, s0, 47
	v_add_u32_e32 v237, v3, v12
	v_lshlrev_b32_e32 v190, 1, v4
	v_writelane_b32 v255, s1, 48
	v_cmp_ge_u32_e64 s[0:1], v20, v16
	v_add_u32_e32 v20, 0x4200, v208
	v_add_u32_e32 v224, v20, v207
	v_writelane_b32 v255, s0, 49
	v_readlane_b32 s50, v254, 30
	s_nop 0
	v_writelane_b32 v255, s1, 50
	v_cmp_ge_u32_e64 s[0:1], v24, v16
	v_or_b32_e32 v24, 0xa00, v0
	v_lshrrev_b32_e32 v178, 5, v24
	v_mad_u32_u24 v25, v178, s42, v8
	v_and_b32_e32 v8, 3, v0
	v_writelane_b32 v255, s46, 51
	v_lshlrev_b32_e32 v29, 8, v8
	v_lshlrev_b32_e32 v31, 7, v8
	v_cmp_eq_u32_e64 s[40:41], 0, v8
	v_writelane_b32 v255, s47, 52
	v_lshl_add_u64 v[8:9], v[148:149], 2, s[68:69]
	s_mov_b64 s[46:47], 0x700000
	v_lshl_add_u64 v[184:185], v[8:9], 0, s[46:47]
	v_and_b32_e32 v8, 0x1fc, v0
	v_add_u32_e32 v212, s45, v8
	v_mbcnt_lo_u32_b32 v8, -1, 0
	v_mbcnt_hi_u32_b32 v8, -1, v8
	v_and_b32_e32 v16, 64, v8
	v_xor_b32_e32 v9, 1, v8
	v_add_u32_e32 v16, 64, v16
	v_cmp_lt_i32_e32 vcc, v9, v16
	s_add_i32 s46, 0, 0x21a00
	v_mad_u32_u24 v24, v178, s42, 0
	v_cndmask_b32_e32 v9, v8, v9, vcc
	v_lshlrev_b32_e32 v213, 2, v9
	v_xor_b32_e32 v9, 2, v8
	v_cmp_lt_i32_e32 vcc, v9, v16
	v_lshl_add_u32 v209, v148, 2, s46
	v_add_u32_e32 v228, v24, v207
	v_cndmask_b32_e32 v9, v8, v9, vcc
	v_lshlrev_b32_e32 v214, 2, v9
	v_xor_b32_e32 v9, 16, v8
	v_cmp_lt_i32_e32 vcc, v9, v16
	v_add_u32_e32 v229, v25, v207
	v_add_u32_e32 v233, v30, v31
	v_cndmask_b32_e32 v9, v8, v9, vcc
	v_lshlrev_b32_e32 v215, 2, v9
	v_xor_b32_e32 v9, 32, v8
	v_cmp_lt_i32_e32 vcc, v9, v16
	s_nop 1
	v_cndmask_b32_e32 v8, v8, v9, vcc
	v_lshlrev_b32_e32 v216, 2, v8
	v_mad_u32_u24 v8, v146, s42, v4
	v_add3_u32 v219, v8, 0, 64
	v_lshlrev_b32_e32 v8, 11, v0
	v_and_b32_e32 v8, 0x6000, v8
	v_and_b32_e32 v148, 0x1c0, v0
	v_lshlrev_b32_e32 v148, 9, v148
	v_and_b32_e32 v9, 0x33, v0
	v_lshl_or_b32 v148, v9, 4, v148
	v_or_b32_e32 v148, v8, v148
	v_lshl_add_u64 v[8:9], s[68:69], 0, v[4:5]
	s_mov_b64 s[42:43], 0x45000000
	v_add_u32_e32 v5, 0, v29
	v_lshl_add_u64 v[186:187], s[68:69], 0, v[148:149]
	v_lshl_add_u64 v[188:189], v[8:9], 0, s[42:43]
	v_add_u32_e32 v234, 0x21a00, v5
	v_lshlrev_b32_e32 v148, 1, v2

.LBB0_584:
	s_or_b64 exec, exec, s[46:47]
	s_lshl_b64 s[46:47], s[44:45], 18
	v_lshl_add_u64 v[10:11], v[150:151], 0, s[46:47]
	v_add_co_u32_e32 v14, vcc, 0x80, v10
	s_waitcnt lgkmcnt(0)
	s_nop 0
	v_addc_co_u32_e32 v15, vcc, 0, v11, vcc
	s_barrier
	global_load_dwordx4 v[2:5], v[10:11], off
	global_load_dwordx4 v[6:9], v[10:11], off offset:64
	s_nop 0
	global_load_dwordx4 v[10:13], v[14:15], off
	s_nop 0
	global_load_dwordx4 v[14:17], v[14:15], off offset:64
	ds_read_b128 v[18:21], v233
	ds_read_b128 v[22:25], v233 offset:16
	ds_read_b128 v[26:29], v233 offset:32
	ds_read_b128 v[30:33], v233 offset:48
	ds_read_b128 v[34:37], v234
	ds_read_b128 v[38:41], v234 offset:16
	ds_read_b128 v[42:45], v234 offset:32
	ds_read_b128 v[46:49], v234 offset:48
	s_waitcnt lgkmcnt(7)
	v_lshlrev_b32_e32 v50, 16, v18
	v_and_b32_e32 v18, 0xffff0000, v18
	s_waitcnt lgkmcnt(3)
	v_mul_f32_e32 v18, v35, v18
	v_fmac_f32_e32 v18, v34, v50
	v_lshlrev_b32_e32 v34, 16, v19
	v_fmac_f32_e32 v18, v36, v34
	v_and_b32_e32 v19, 0xffff0000, v19
	v_fmac_f32_e32 v18, v37, v19
	v_lshlrev_b32_e32 v19, 16, v20
	s_waitcnt lgkmcnt(2)
	v_fmac_f32_e32 v18, v38, v19
	v_and_b32_e32 v19, 0xffff0000, v20
	v_fmac_f32_e32 v18, v39, v19
	v_lshlrev_b32_e32 v19, 16, v21
	v_fmac_f32_e32 v18, v40, v19
	v_and_b32_e32 v19, 0xffff0000, v21
	v_fmac_f32_e32 v18, v41, v19
	v_and_b32_e32 v19, 0xffff0000, v22
	v_add_f32_e32 v34, 0, v18
	v_lshlrev_b32_e32 v18, 16, v22
	s_waitcnt lgkmcnt(1)
	v_mul_f32_e32 v22, v43, v19
	v_fmac_f32_e32 v22, v42, v18
	v_lshlrev_b32_e32 v18, 16, v23
	v_fmac_f32_e32 v22, v44, v18
	v_and_b32_e32 v18, 0xffff0000, v23
	v_fmac_f32_e32 v22, v45, v18
	v_lshlrev_b32_e32 v18, 16, v24
	s_waitcnt lgkmcnt(0)
	v_fmac_f32_e32 v22, v46, v18
	v_and_b32_e32 v18, 0xffff0000, v24
	v_fmac_f32_e32 v22, v47, v18
	v_lshlrev_b32_e32 v18, 16, v25
	v_fmac_f32_e32 v22, v48, v18
	v_and_b32_e32 v18, 0xffff0000, v25
	v_fmac_f32_e32 v22, v49, v18
	ds_read_b128 v[18:21], v234 offset:64
	v_add_f32_e32 v34, v34, v22
	ds_read_b128 v[22:25], v234 offset:80
	v_lshlrev_b32_e32 v35, 16, v26
	v_and_b32_e32 v26, 0xffff0000, v26
	s_waitcnt lgkmcnt(1)
	v_mul_f32_e32 v26, v19, v26
	v_fmac_f32_e32 v26, v18, v35
	v_lshlrev_b32_e32 v18, 16, v27
	v_fmac_f32_e32 v26, v20, v18
	v_and_b32_e32 v18, 0xffff0000, v27
	v_fmac_f32_e32 v26, v21, v18
	v_lshlrev_b32_e32 v18, 16, v28
	s_waitcnt lgkmcnt(0)
	v_fmac_f32_e32 v26, v22, v18
	v_and_b32_e32 v18, 0xffff0000, v28
	v_fmac_f32_e32 v26, v23, v18
	v_lshlrev_b32_e32 v18, 16, v29
	v_fmac_f32_e32 v26, v24, v18
	v_and_b32_e32 v18, 0xffff0000, v29
	v_fmac_f32_e32 v26, v25, v18
	ds_read_b128 v[18:21], v234 offset:96
	ds_read_b128 v[22:25], v234 offset:112
	v_and_b32_e32 v28, 0xffff0000, v30
	v_lshlrev_b32_e32 v27, 16, v30
	v_add_f32_e32 v26, v34, v26
	s_waitcnt lgkmcnt(1)
	v_mul_f32_e32 v28, v19, v28
	v_fmac_f32_e32 v28, v18, v27
	v_lshlrev_b32_e32 v18, 16, v31
	v_fmac_f32_e32 v28, v20, v18
	v_and_b32_e32 v18, 0xffff0000, v31
	v_fmac_f32_e32 v28, v21, v18
	v_lshlrev_b32_e32 v18, 16, v32
	s_waitcnt lgkmcnt(0)
	v_fmac_f32_e32 v28, v22, v18
	v_and_b32_e32 v18, 0xffff0000, v32
	v_fmac_f32_e32 v28, v23, v18
	v_lshlrev_b32_e32 v18, 16, v33
	v_fmac_f32_e32 v28, v24, v18
	v_and_b32_e32 v18, 0xffff0000, v33
	v_fmac_f32_e32 v28, v25, v18
	ds_read_b128 v[18:21], v233 offset:64
	v_add_f32_e32 v34, v26, v28
	ds_read_b128 v[22:25], v234 offset:128
	ds_read_b128 v[26:29], v234 offset:144
	ds_read_b128 v[30:33], v233 offset:80
	s_waitcnt lgkmcnt(3)
	v_lshlrev_b32_e32 v35, 16, v18
	v_and_b32_e32 v18, 0xffff0000, v18
	s_waitcnt lgkmcnt(2)
	v_mul_f32_e32 v23, v23, v18
	v_fmac_f32_e32 v23, v22, v35
	v_lshlrev_b32_e32 v18, 16, v19
	v_fmac_f32_e32 v23, v24, v18
	v_and_b32_e32 v18, 0xffff0000, v19
	v_fmac_f32_e32 v23, v25, v18
	v_lshlrev_b32_e32 v18, 16, v20
	s_waitcnt lgkmcnt(1)
	v_fmac_f32_e32 v23, v26, v18
	v_and_b32_e32 v18, 0xffff0000, v20
	v_fmac_f32_e32 v23, v27, v18
	v_lshlrev_b32_e32 v18, 16, v21
	v_fmac_f32_e32 v23, v28, v18
	v_and_b32_e32 v18, 0xffff0000, v21
	v_fmac_f32_e32 v23, v29, v18
	ds_read_b128 v[18:21], v234 offset:160
	v_add_f32_e32 v26, v34, v23
	ds_read_b128 v[22:25], v234 offset:176
	s_waitcnt lgkmcnt(2)
	v_and_b32_e32 v28, 0xffff0000, v30
	v_lshlrev_b32_e32 v27, 16, v30
	s_waitcnt lgkmcnt(1)
	v_mul_f32_e32 v28, v19, v28
	v_fmac_f32_e32 v28, v18, v27
	v_lshlrev_b32_e32 v18, 16, v31
	v_fmac_f32_e32 v28, v20, v18
	v_and_b32_e32 v18, 0xffff0000, v31
	v_fmac_f32_e32 v28, v21, v18
	v_lshlrev_b32_e32 v18, 16, v32
	s_waitcnt lgkmcnt(0)
	v_fmac_f32_e32 v28, v22, v18
	v_and_b32_e32 v18, 0xffff0000, v32
	v_fmac_f32_e32 v28, v23, v18
	v_lshlrev_b32_e32 v18, 16, v33
	v_fmac_f32_e32 v28, v24, v18
	v_and_b32_e32 v18, 0xffff0000, v33
	v_fmac_f32_e32 v28, v25, v18
	ds_read_b128 v[18:21], v233 offset:96
	v_add_f32_e32 v34, v26, v28
	ds_read_b128 v[22:25], v234 offset:192
	ds_read_b128 v[26:29], v234 offset:208
	ds_read_b128 v[30:33], v233 offset:112
	s_waitcnt lgkmcnt(3)
	v_lshlrev_b32_e32 v35, 16, v18
	v_and_b32_e32 v18, 0xffff0000, v18
	s_waitcnt lgkmcnt(2)
	v_mul_f32_e32 v23, v23, v18
	v_fmac_f32_e32 v23, v22, v35
	v_lshlrev_b32_e32 v18, 16, v19
	v_fmac_f32_e32 v23, v24, v18
	v_and_b32_e32 v18, 0xffff0000, v19
	v_fmac_f32_e32 v23, v25, v18
	v_lshlrev_b32_e32 v18, 16, v20
	s_waitcnt lgkmcnt(1)
	v_fmac_f32_e32 v23, v26, v18
	v_and_b32_e32 v18, 0xffff0000, v20
	v_fmac_f32_e32 v23, v27, v18
	v_lshlrev_b32_e32 v18, 16, v21
	v_fmac_f32_e32 v23, v28, v18
	v_and_b32_e32 v18, 0xffff0000, v21
	v_fmac_f32_e32 v23, v29, v18
	ds_read_b128 v[18:21], v234 offset:224
	v_add_f32_e32 v26, v34, v23
	ds_read_b128 v[22:25], v234 offset:240
	s_waitcnt lgkmcnt(2)
	v_and_b32_e32 v28, 0xffff0000, v30
	v_lshlrev_b32_e32 v27, 16, v30
	s_waitcnt lgkmcnt(1)
	v_mul_f32_e32 v19, v19, v28
	v_fmac_f32_e32 v19, v18, v27
	v_lshlrev_b32_e32 v18, 16, v31
	v_fmac_f32_e32 v19, v20, v18
	v_and_b32_e32 v18, 0xffff0000, v31
	v_fmac_f32_e32 v19, v21, v18
	v_lshlrev_b32_e32 v18, 16, v32
	s_waitcnt lgkmcnt(0)
	v_fmac_f32_e32 v19, v22, v18
	v_and_b32_e32 v18, 0xffff0000, v32
	v_fmac_f32_e32 v19, v23, v18
	v_lshlrev_b32_e32 v18, 16, v33
	v_fmac_f32_e32 v19, v24, v18
	v_and_b32_e32 v18, 0xffff0000, v33
	v_fmac_f32_e32 v19, v25, v18
	v_add_f32_e32 v18, v26, v19
	ds_bpermute_b32 v19, v213, v18
	s_waitcnt lgkmcnt(0)
	v_add_f32_e32 v18, v18, v19
	ds_bpermute_b32 v19, v214, v18
	s_and_saveexec_b64 s[44:45], s[40:41]
	s_cbranch_execz .LBB0_586
	s_waitcnt lgkmcnt(0)
	v_add_f32_e32 v18, v18, v19
	ds_write_b32 v212, v18

.LBB0_593:
	v_lshl_add_u64 v[142:143], v[10:11], 0, s[42:43]
	s_mov_b32 s44, 0x1000000
	v_add_co_u32_e32 v192, vcc, s44, v142
	s_mov_b32 s44, 0x1000080
	s_nop 0
	v_addc_co_u32_e32 v193, vcc, 0, v143, vcc
	v_add_co_u32_e32 v242, vcc, s44, v142
	ds_read_b128 v[134:137], v12
	ds_read_b128 v[138:141], v12 offset:8448
	v_addc_co_u32_e32 v243, vcc, 0, v143, vcc
	global_load_dwordx4 v[142:145], v[192:193], off offset:1024
	s_nop 0
	global_load_dwordx4 v[192:195], v[192:193], off offset:1088
	s_add_u32 s42, s42, 0x400
	global_load_dwordx4 v[238:241], v[242:243], off offset:1024
	s_addc_u32 s43, s43, 0
	global_load_dwordx4 v[242:245], v[242:243], off offset:1088
	s_cmpk_lg_i32 s42, 0x1c00
	s_waitcnt vmcnt(3) lgkmcnt(1)
	v_mfma_f32_16x16x32_bf16 v[114:117], v[142:145], v[134:137], v[114:117]
	s_waitcnt vmcnt(2)
	v_mfma_f32_16x16x32_bf16 v[118:121], v[192:195], v[134:137], v[118:121]
	s_waitcnt vmcnt(1)
	v_mfma_f32_16x16x32_bf16 v[122:125], v[238:241], v[134:137], v[122:125]
	s_waitcnt vmcnt(0)
	v_mfma_f32_16x16x32_bf16 v[126:129], v[242:245], v[134:137], v[126:129]
	s_waitcnt lgkmcnt(0)
	v_mfma_f32_16x16x32_bf16 v[106:109], v[142:145], v[138:141], v[106:109]
	v_mfma_f32_16x16x32_bf16 v[110:113], v[192:195], v[138:141], v[110:113]
	v_mfma_f32_16x16x32_bf16 v[102:105], v[238:241], v[138:141], v[102:105]
	v_mfma_f32_16x16x32_bf16 v[98:101], v[242:245], v[138:141], v[98:101]
	ds_read_b128 v[134:137], v12 offset:16896
	ds_read_b128 v[138:141], v12 offset:25344
	s_waitcnt lgkmcnt(1)
	v_mfma_f32_16x16x32_bf16 v[82:85], v[142:145], v[134:137], v[82:85]
	v_mfma_f32_16x16x32_bf16 v[86:89], v[192:195], v[134:137], v[86:89]
	v_mfma_f32_16x16x32_bf16 v[90:93], v[238:241], v[134:137], v[90:93]
	v_mfma_f32_16x16x32_bf16 v[94:97], v[242:245], v[134:137], v[94:97]
	s_waitcnt lgkmcnt(0)
	v_mfma_f32_16x16x32_bf16 v[74:77], v[142:145], v[138:141], v[74:77]
	v_mfma_f32_16x16x32_bf16 v[78:81], v[192:195], v[138:141], v[78:81]
	v_mfma_f32_16x16x32_bf16 v[70:73], v[238:241], v[138:141], v[70:73]
	v_mfma_f32_16x16x32_bf16 v[66:69], v[242:245], v[138:141], v[66:69]
	ds_read_b128 v[134:137], v12 offset:33792
	ds_read_b128 v[138:141], v12 offset:42240
	s_waitcnt lgkmcnt(1)
	v_mfma_f32_16x16x32_bf16 v[50:53], v[142:145], v[134:137], v[50:53]
	v_mfma_f32_16x16x32_bf16 v[58:61], v[192:195], v[134:137], v[58:61]
	v_mfma_f32_16x16x32_bf16 v[54:57], v[238:241], v[134:137], v[54:57]
	v_mfma_f32_16x16x32_bf16 v[62:65], v[242:245], v[134:137], v[62:65]
	s_waitcnt lgkmcnt(0)
	v_mfma_f32_16x16x32_bf16 v[42:45], v[142:145], v[138:141], v[42:45]
	v_mfma_f32_16x16x32_bf16 v[46:49], v[192:195], v[138:141], v[46:49]
	v_mfma_f32_16x16x32_bf16 v[38:41], v[238:241], v[138:141], v[38:41]
	v_mfma_f32_16x16x32_bf16 v[34:37], v[242:245], v[138:141], v[34:37]
	ds_read_b128 v[134:137], v12 offset:50688
	ds_read_b128 v[138:141], v12 offset:59136
	v_add_u32_e32 v12, 64, v12
	s_waitcnt lgkmcnt(1)
	v_mfma_f32_16x16x32_bf16 v[18:21], v[142:145], v[134:137], v[18:21]
	v_mfma_f32_16x16x32_bf16 v[22:25], v[192:195], v[134:137], v[22:25]
	v_mfma_f32_16x16x32_bf16 v[26:29], v[238:241], v[134:137], v[26:29]
	v_mfma_f32_16x16x32_bf16 v[30:33], v[242:245], v[134:137], v[30:33]
	s_waitcnt lgkmcnt(0)
	v_mfma_f32_16x16x32_bf16 v[2:5], v[142:145], v[138:141], v[2:5]
	v_mfma_f32_16x16x32_bf16 v[130:133], v[192:195], v[138:141], v[130:133]
	v_mfma_f32_16x16x32_bf16 v[6:9], v[238:241], v[138:141], v[6:9]
	v_mfma_f32_16x16x32_bf16 v[14:17], v[242:245], v[138:141], v[14:17]
	s_cbranch_scc1 .LBB0_593
	ds_read2_b32 v[192:193], v147 offset1:16
	s_lshl_b32 s42, s81, 9
	s_lshl_b64 s[44:45], s[62:63], 13
	s_mov_b32 s43, 0
	s_waitcnt lgkmcnt(0)
	v_mov_b32_e32 v10, v193
	v_pk_mul_f32 v[108:109], v[108:109], v[10:11] op_sel_hi:[1,0]
	v_pk_mul_f32 v[106:107], v[106:107], v[10:11] op_sel_hi:[1,0]
	v_pk_mul_f32 v[112:113], v[112:113], v[10:11] op_sel_hi:[1,0]
	v_pk_mul_f32 v[110:111], v[110:111], v[10:11] op_sel_hi:[1,0]
	v_pk_mul_f32 v[104:105], v[104:105], v[10:11] op_sel_hi:[1,0]
	v_pk_mul_f32 v[102:103], v[102:103], v[10:11] op_sel_hi:[1,0]
	v_pk_mul_f32 v[100:101], v[100:101], v[10:11] op_sel_hi:[1,0]
	v_pk_mul_f32 v[98:99], v[98:99], v[10:11] op_sel_hi:[1,0]
	ds_read2_b32 v[10:11], v147 offset0:32 offset1:48
	v_pk_mul_f32 v[116:117], v[116:117], v[192:193] op_sel_hi:[1,0]
	v_pk_mul_f32 v[114:115], v[114:115], v[192:193] op_sel_hi:[1,0]
	v_pk_mul_f32 v[120:121], v[120:121], v[192:193] op_sel_hi:[1,0]
	v_pk_mul_f32 v[118:119], v[118:119], v[192:193] op_sel_hi:[1,0]
	s_waitcnt lgkmcnt(0)
	v_pk_mul_f32 v[84:85], v[84:85], v[10:11] op_sel_hi:[1,0]
	v_pk_mul_f32 v[82:83], v[82:83], v[10:11] op_sel_hi:[1,0]
	v_pk_mul_f32 v[88:89], v[88:89], v[10:11] op_sel_hi:[1,0]
	v_pk_mul_f32 v[86:87], v[86:87], v[10:11] op_sel_hi:[1,0]
	v_pk_mul_f32 v[92:93], v[92:93], v[10:11] op_sel_hi:[1,0]
	v_pk_mul_f32 v[90:91], v[90:91], v[10:11] op_sel_hi:[1,0]
	v_pk_mul_f32 v[96:97], v[96:97], v[10:11] op_sel_hi:[1,0]
	v_pk_mul_f32 v[94:95], v[94:95], v[10:11] op_sel_hi:[1,0]
	v_mov_b32_e32 v10, v11
	v_pk_mul_f32 v[76:77], v[76:77], v[10:11] op_sel_hi:[1,0]
	v_pk_mul_f32 v[74:75], v[74:75], v[10:11] op_sel_hi:[1,0]
	v_pk_mul_f32 v[80:81], v[80:81], v[10:11] op_sel_hi:[1,0]
	v_pk_mul_f32 v[78:79], v[78:79], v[10:11] op_sel_hi:[1,0]
	v_pk_mul_f32 v[72:73], v[72:73], v[10:11] op_sel_hi:[1,0]
	v_pk_mul_f32 v[70:71], v[70:71], v[10:11] op_sel_hi:[1,0]
	v_pk_mul_f32 v[68:69], v[68:69], v[10:11] op_sel_hi:[1,0]
	v_pk_mul_f32 v[66:67], v[66:67], v[10:11] op_sel_hi:[1,0]
	ds_read2_b32 v[10:11], v147 offset0:64 offset1:80
	v_pk_mul_f32 v[124:125], v[124:125], v[192:193] op_sel_hi:[1,0]
	v_pk_mul_f32 v[122:123], v[122:123], v[192:193] op_sel_hi:[1,0]
	v_pk_mul_f32 v[128:129], v[128:129], v[192:193] op_sel_hi:[1,0]
	v_pk_mul_f32 v[126:127], v[126:127], v[192:193] op_sel_hi:[1,0]
	s_waitcnt lgkmcnt(0)
	v_pk_mul_f32 v[52:53], v[52:53], v[10:11] op_sel_hi:[1,0]
	v_pk_mul_f32 v[50:51], v[50:51], v[10:11] op_sel_hi:[1,0]
	v_pk_mul_f32 v[60:61], v[60:61], v[10:11] op_sel_hi:[1,0]
	v_pk_mul_f32 v[58:59], v[58:59], v[10:11] op_sel_hi:[1,0]
	v_pk_mul_f32 v[56:57], v[56:57], v[10:11] op_sel_hi:[1,0]
	v_pk_mul_f32 v[54:55], v[54:55], v[10:11] op_sel_hi:[1,0]
	v_pk_mul_f32 v[64:65], v[64:65], v[10:11] op_sel_hi:[1,0]
	v_pk_mul_f32 v[62:63], v[62:63], v[10:11] op_sel_hi:[1,0]
	v_mov_b32_e32 v10, v11
	v_pk_mul_f32 v[44:45], v[44:45], v[10:11] op_sel_hi:[1,0]
	v_pk_mul_f32 v[42:43], v[42:43], v[10:11] op_sel_hi:[1,0]
	v_pk_mul_f32 v[48:49], v[48:49], v[10:11] op_sel_hi:[1,0]
	v_pk_mul_f32 v[46:47], v[46:47], v[10:11] op_sel_hi:[1,0]
	v_pk_mul_f32 v[40:41], v[40:41], v[10:11] op_sel_hi:[1,0]
	v_pk_mul_f32 v[38:39], v[38:39], v[10:11] op_sel_hi:[1,0]
	v_pk_mul_f32 v[36:37], v[36:37], v[10:11] op_sel_hi:[1,0]
	v_pk_mul_f32 v[34:35], v[34:35], v[10:11] op_sel_hi:[1,0]
	ds_read2_b32 v[10:11], v147 offset0:96 offset1:112
	s_waitcnt lgkmcnt(0)
	v_mov_b32_e32 v134, v11
	v_pk_mul_f32 v[20:21], v[20:21], v[10:11] op_sel_hi:[1,0]
	v_pk_mul_f32 v[18:19], v[18:19], v[10:11] op_sel_hi:[1,0]
	v_pk_mul_f32 v[24:25], v[24:25], v[10:11] op_sel_hi:[1,0]
	v_pk_mul_f32 v[22:23], v[22:23], v[10:11] op_sel_hi:[1,0]
	v_pk_mul_f32 v[28:29], v[28:29], v[10:11] op_sel_hi:[1,0]
	v_pk_mul_f32 v[26:27], v[26:27], v[10:11] op_sel_hi:[1,0]
	v_pk_mul_f32 v[32:33], v[32:33], v[10:11] op_sel_hi:[1,0]
	v_pk_mul_f32 v[30:31], v[30:31], v[10:11] op_sel_hi:[1,0]
	v_pk_mul_f32 v[10:11], v[130:131], v[134:135] op_sel_hi:[1,0]
	v_or_b32_e32 v130, s42, v1
	v_lshlrev_b32_e32 v130, 15, v130
	v_mov_b32_e32 v131, v149
	v_lshl_add_u64 v[130:131], v[130:131], 0, s[44:45]
	v_lshl_or_b32 v130, s80, 8, v130
	v_pk_mul_f32 v[4:5], v[4:5], v[134:135] op_sel_hi:[1,0]
	v_pk_mul_f32 v[2:3], v[2:3], v[134:135] op_sel_hi:[1,0]
	v_pk_mul_f32 v[12:13], v[132:133], v[134:135] op_sel_hi:[1,0]
	v_pk_mul_f32 v[8:9], v[8:9], v[134:135] op_sel_hi:[1,0]
	v_pk_mul_f32 v[6:7], v[6:7], v[134:135] op_sel_hi:[1,0]
	v_pk_mul_f32 v[16:17], v[16:17], v[134:135] op_sel_hi:[1,0]
	v_pk_mul_f32 v[14:15], v[14:15], v[134:135] op_sel_hi:[1,0]
	v_lshl_add_u64 v[194:195], v[188:189], 0, v[130:131]
